# FFN1 k-loop only: two k-tiles in flight instead of three (prologue requests 2 tiles, in-loop request is tile kt+2, wait vmcnt(5)); FFN2 and attention-output loops keep three
# speedup vs baseline: 1.0545x; 1.0091x over previous
; #define G3_TILE(kt_, st_) do { const size_t ko_ = (size_t)(kt_) * 1024; unsigned char* d_ = smem + (st_) * 20480; \
;         _Pragma("unroll") for (int s_ = 0; s_ < 12; ++s_) GLDS16(Abase + (size_t)s_ * ksub + ko_ + voff, d_ + s_ * 1024); \
;         _Pragma("unroll") for (int s_ = 0; s_ < 8; ++s_) GLDS16(Bbase + (size_t)s_ * ksub + ko_ + voff, d_ + 12288 + s_ * 1024); } while (0)
; template <int EPI>
; __device__ __forceinline__ void gemm_tile3(const Params& p, int l, const u16* __restrict__ A, int lda, const u16* __restrict__ Bt, int K, int m0, int n0, unsigned char* smem) {
;     ...
;     const int nk = K >> 5;
;     if (wid < 3) G3_TILE(wid, wid);
;     const unsigned char* fa = smem + (wr * 6) * 1024 + fr * 64 + fq * 16;
;     const unsigned char* fb = smem + 12288 + (wc * 4) * 1024 + fr * 64 + fq * 16;
;     int st = 0, stn = 3;
;     if (wid == 0) asm volatile("s_waitcnt vmcnt(0)" ::: "memory");
;     asm volatile("s_waitcnt lgkmcnt(0)" ::: "memory");
;     __builtin_amdgcn_s_barrier();
;     asm volatile("" ::: "memory");
;     for (int kt = 0; kt < nk; ++kt) {
;         if (((kt + 1) & 3) == wid && kt + 1 < nk) asm volatile("s_waitcnt vmcnt(0)" ::: "memory");
;         __builtin_amdgcn_s_barrier();
;         asm volatile("" ::: "memory");
;         if (((kt + 3) & 3) == wid && kt + 3 < nk) G3_TILE(kt + 3, stn);
.Lf1_pro:
	s_add_i32 s17, s51, s54
	s_add_i32 s18, s51, s0
	s_mov_b32 m0, s17
	s_add_i32 s17, s17, 0x400
	global_load_lds_dwordx4 v252, s[28:29]
	s_mov_b32 m0, s17
	s_add_i32 s17, s17, 0x400
	global_load_lds_dwordx4 v253, s[28:29]
	s_mov_b32 m0, s17
	s_nop 0
	global_load_lds_dwordx4 v254, s[28:29]
	s_mov_b32 m0, s18
	s_add_i32 s18, s18, 0x400
	global_load_lds_dwordx4 v252, s[30:31]
	s_mov_b32 m0, s18
	s_add_u32 s28, s28, 0x400
	global_load_lds_dwordx4 v253, s[30:31]
	s_addc_u32 s29, s29, 0
	s_add_u32 s30, s30, 0x400
	s_addc_u32 s31, s31, 0
	s_add_i32 s51, s51, 0x5000
	s_cmp_lg_u32 s51, 0xa000
	s_cbranch_scc1 .Lf1_pro
	v_ashrrev_i32_e32 v99, 7, v106
	s_movk_i32 s17, 0x1800
	v_and_b32_e32 v103, 15, v106
	v_mul_lo_u32 v2, v99, s17
	v_and_b32_e32 v107, 1, v98
	v_lshlrev_b32_e32 v102, 6, v103
	v_and_b32_e32 v3, 48, v106
	v_and_b32_e32 v4, 8, v106
	v_lshlrev_b32_e32 v4, 2, v4
	v_xor_b32_e32 v3, v3, v4
	v_add3_u32 v108, v2, v102, v3
	v_lshlrev_b32_e32 v2, 12, v107
	v_add3_u32 v109, v2, v102, v3
	s_waitcnt lgkmcnt(0)
	v_mov_b32_e32 v2, 0
	v_mov_b32_e32 v3, v2
	v_mov_b32_e32 v4, v2
	v_mov_b32_e32 v5, v2
	v_mov_b32_e32 v6, v2
	v_mov_b32_e32 v7, v2
	v_mov_b32_e32 v8, v2
	v_mov_b32_e32 v9, v2
	v_mov_b32_e32 v10, v2
	v_mov_b32_e32 v11, v2
	v_mov_b32_e32 v12, v2
	v_mov_b32_e32 v13, v2
	v_mov_b32_e32 v14, v2
	v_mov_b32_e32 v15, v2
	v_mov_b32_e32 v16, v2
	v_mov_b32_e32 v17, v2
	v_mov_b32_e32 v22, v2
	v_mov_b32_e32 v23, v2
	v_mov_b32_e32 v24, v2
	v_mov_b32_e32 v25, v2
	v_mov_b32_e32 v18, v2
	v_mov_b32_e32 v19, v2
	v_mov_b32_e32 v20, v2
	v_mov_b32_e32 v21, v2
	v_mov_b32_e32 v26, v2
	v_mov_b32_e32 v27, v2
	v_mov_b32_e32 v28, v2
	v_mov_b32_e32 v29, v2
	v_mov_b32_e32 v30, v2
	v_mov_b32_e32 v31, v2
	v_mov_b32_e32 v32, v2
	v_mov_b32_e32 v33, v2
	v_mov_b32_e32 v38, v2
	v_mov_b32_e32 v39, v2
	v_mov_b32_e32 v40, v2
	v_mov_b32_e32 v41, v2
	v_mov_b32_e32 v34, v2
	v_mov_b32_e32 v35, v2
	v_mov_b32_e32 v36, v2
	v_mov_b32_e32 v37, v2
	v_mov_b32_e32 v42, v2
	v_mov_b32_e32 v43, v2
	v_mov_b32_e32 v44, v2
	v_mov_b32_e32 v45, v2
	v_mov_b32_e32 v46, v2
	v_mov_b32_e32 v47, v2
	v_mov_b32_e32 v48, v2
	v_mov_b32_e32 v49, v2
	v_mov_b32_e32 v54, v2
	v_mov_b32_e32 v55, v2
	v_mov_b32_e32 v56, v2
	v_mov_b32_e32 v57, v2
	v_mov_b32_e32 v50, v2
	v_mov_b32_e32 v51, v2
	v_mov_b32_e32 v52, v2
	v_mov_b32_e32 v53, v2
	v_mov_b32_e32 v58, v2
	v_mov_b32_e32 v59, v2
	v_mov_b32_e32 v60, v2
	v_mov_b32_e32 v61, v2
	v_mov_b32_e32 v62, v2
	v_mov_b32_e32 v63, v2
	v_mov_b32_e32 v64, v2
	v_mov_b32_e32 v65, v2
	v_mov_b32_e32 v70, v2
	v_mov_b32_e32 v71, v2
	v_mov_b32_e32 v72, v2
	v_mov_b32_e32 v73, v2
	v_mov_b32_e32 v66, v2
	v_mov_b32_e32 v67, v2
	v_mov_b32_e32 v68, v2
	v_mov_b32_e32 v69, v2
	v_mov_b32_e32 v74, v2
	v_mov_b32_e32 v75, v2
	v_mov_b32_e32 v76, v2
	v_mov_b32_e32 v77, v2
	v_mov_b32_e32 v78, v2
	v_mov_b32_e32 v79, v2
	v_mov_b32_e32 v80, v2
	v_mov_b32_e32 v81, v2
	v_mov_b32_e32 v82, v2
	v_mov_b32_e32 v83, v2
	v_mov_b32_e32 v84, v2
	v_mov_b32_e32 v85, v2
	v_mov_b32_e32 v86, v2
	v_mov_b32_e32 v87, v2
	v_mov_b32_e32 v88, v2
	v_mov_b32_e32 v89, v2
	v_mov_b32_e32 v90, v2
	v_mov_b32_e32 v91, v2
	v_mov_b32_e32 v92, v2
	v_mov_b32_e32 v93, v2
	v_mov_b32_e32 v94, v2
	v_mov_b32_e32 v95, v2
	v_mov_b32_e32 v96, v2
	v_mov_b32_e32 v97, v2
	s_mov_b32 s16, 0
	s_mov_b32 s50, 0
	v_add_u32_e32 v110, s50, v109
	v_add_u32_e32 v122, 0x3000, v110
	v_add_u32_e32 v0, s50, v108
	s_branch .Lf1_head
.Lf1_w5:
	s_waitcnt vmcnt(5)
	s_branch .Lf1_bar
.Lf1_head:
	s_waitcnt vmcnt(5)
.Lf1_bar:
	s_barrier
	ds_read_b128 v[110:113], v122 offset:0
	ds_read_b128 v[114:117], v122 offset:1024
	ds_read_b128 v[118:121], v122 offset:2048
	ds_read_b128 v[122:125], v122 offset:3072
	ds_read_b128 v[126:129], v0 offset:0
	ds_read_b128 v[130:133], v0 offset:1024
	ds_read_b128 v[134:137], v0 offset:2048
	ds_read_b128 v[138:141], v0 offset:3072
	ds_read_b128 v[142:145], v0 offset:4096
	ds_read_b128 v[146:149], v0 offset:5120
	s_cmp_lt_u32 s16, 30
	s_cbranch_scc0 .Lf1_mm
	s_add_i32 s17, s51, s54
	s_add_i32 s18, s51, s0
	s_mov_b32 m0, s17
	s_add_i32 s17, s17, 0x400
	global_load_lds_dwordx4 v252, s[28:29]
	s_mov_b32 m0, s17
	s_add_i32 s17, s17, 0x400
	global_load_lds_dwordx4 v253, s[28:29]
	s_mov_b32 m0, s17
	s_nop 0
	global_load_lds_dwordx4 v254, s[28:29]
	s_mov_b32 m0, s18
	s_add_i32 s18, s18, 0x400
	global_load_lds_dwordx4 v252, s[30:31]
	s_mov_b32 m0, s18
	s_add_u32 s28, s28, 0x400
	global_load_lds_dwordx4 v253, s[30:31]
	s_addc_u32 s29, s29, 0
	s_add_u32 s30, s30, 0x400
	s_addc_u32 s31, s31, 0
	s_add_i32 s51, s51, 0x5000
	s_cmp_eq_u32 s51, 0x14000
	s_cselect_b32 s51, 0, s51
